# P8 row-stat exchange: dropped the per-tile L2 writeback (only memory-side atomics are published before the arrival counter)
# speedup vs baseline: 1.0298x; 1.0049x over previous
;     __device__ __forceinline__ void operator()(EPI_ARGS) const {
;     ...
;         asm volatile("s_waitcnt vmcnt(0)" ::: "memory"); __builtin_amdgcn_s_barrier(); asm volatile("" ::: "memory");
;         if (threadIdx.x == 0) {
;             __builtin_amdgcn_fence(__ATOMIC_RELEASE, "agent");
;             __hip_atomic_fetch_add(cnt + u.pm, 1u, __ATOMIC_RELAXED, __HIP_MEMORY_SCOPE_AGENT);
;             unsigned sp = 0;
;             while (__hip_atomic_load(cnt + u.pm, __ATOMIC_RELAXED, __HIP_MEMORY_SCOPE_AGENT) < 8u) { __builtin_amdgcn_s_sleep(1); if (++sp > (1u << 22)) break; }
.LBB0_1322:
	s_or_b64 exec, exec, s[8:9]
	s_waitcnt vmcnt(0)
	s_barrier
	s_and_saveexec_b64 s[8:9], s[56:57]
	s_cbranch_execz .LBB0_1334
	s_mov_b64 s[12:13], exec
	s_ashr_i32 s27, s26, 31
	s_lshl_b64 s[10:11], s[26:27], 2
	v_mbcnt_lo_u32_b32 v0, s12, 0
	s_add_u32 s10, s35, s10
	v_mbcnt_hi_u32_b32 v0, s13, v0
	s_addc_u32 s11, s36, s11
	v_cmp_eq_u32_e32 vcc, 0, v0
	s_waitcnt vmcnt(0) lgkmcnt(0)
	s_and_saveexec_b64 s[26:27], vcc
	s_cbranch_execz .LBB0_1325
	s_bcnt1_i32_b64 s7, s[12:13]
	v_mov_b32_e32 v0, s7
	global_atomic_add v129, v0, s[10:11]
